# attention loop v2: exps spread in groups of 4 between the PV MFMAs (each group followed by its partial sums and packs)
# baseline (speedup 1.0000x reference)
; #define LAS __attribute__((address_space(3)))
; #define SB0() __builtin_amdgcn_sched_barrier(0)
; template <bool SHIFT> DI void attn_unit(LAS unsigned char* lds, const bf16_t* Qb, const bf16_t* Kb, const bf16_t* Vt, bf16_t* concat,
;                   int b, int h, int qt, float shift2, float lam, int lam_init_bits, const float* subln_g) {
;     ...
;     for (int kt = 0; kt < nkt; ++kt) {
;         const int cur = kt & 1, nx = cur ^ 1;
;         const int vnx = vcur == 2 ? 0 : vcur + 1;
;         const bool pf = (kt + 1 < nkt);
;         const size_t ko = (size_t)(kt + 1) * 64;
;         if (pf) { *(LAS u32x4*)(lds + K_OFF + nx * K_BYTES + krow0 * QP + kc * 16) = sg0; *(LAS u32x4*)(lds + K_OFF + nx * K_BYTES + (krow0 + 32) * QP + kc * 16) = sg1;
;             sg0 = *(const u32x4*)(vg + (size_t)(vrow0) * TPB + ko + vc * 8); sg1 = *(const u32x4*)(vg + (size_t)(vrow0 + 64) * TPB + ko + vc * 8); }
;         const LAS unsigned char* kb = lds + K_OFF + cur * K_BYTES + r * QP + hh * 16;
;         const LAS unsigned char* vb = lds + V_OFF + vcur * V_BYTES + r * VP + hh * 16;
; #pragma unroll
;         for (int half = 0; half < 2; ++half) {
;             if (lag) PVH(Pc, vold);
;             QKEXP(Pc, half);
;             if (half == 0 && pf) { *(LAS u32x4*)(lds + V_OFF + vnx * V_BYTES + vrow0 * VP + vc * 16) = sg0; *(LAS u32x4*)(lds + V_OFF + vnx * V_BYTES + (vrow0 + 64) * VP + vc * 16) = sg1;
;                 if (kt + 2 < nkt) { sg0 = *(const u32x4*)(kg + (ko + 64 + krow0) * 1024 + kc * 8); sg1 = *(const u32x4*)(kg + (ko + 64 + krow0 + 32) * 1024 + kc * 8); } }
;             vold = vb + half * 64;
;             SB0();
;             if (!lag) PVH(Pc, vold);
;         }
.LBB0_533:
	s_and_b32 s6, s34, 1
	s_xor_b32 s4, s6, 1
	s_mulk_i32 s4, 0x4400
	s_add_i32 s4, s4, 0x11000
	v_add3_u32 v137, s4, v210, v160
	v_add3_u32 v142, s4, v214, v160
	s_mulk_i32 s6, 0x4400
	v_add_u32_e32 v254, s6, v212
	s_mul_i32 s6, s40, 0x4800
	v_add_u32_e32 v217, s6, v213
	ds_read_b128 v[178:181], v254
	ds_read_b128 v[186:189], v211
	ds_read_b128 v[182:185], v254 offset:32
	ds_read_b128 v[190:193], v211 offset:32
	ds_read_b128 v[228:231], v136
	ds_read_b128 v[232:235], v136 offset:4608
	s_add_i32 s7, s40, 1
	s_cmp_lg_u32 s40, 2
	s_cselect_b32 s65, s7, 0
	s_mul_i32 s37, s65, 0x4800
	s_add_i32 s6, s37, 0x19800
	v_add3_u32 v218, s6, v215, v176
	v_add3_u32 v219, s6, v216, v176
	v_add_co_u32_e32 v138, vcc, 0xffef8000, v168
	s_andn2_b64 s[4:5], exec, s[18:19]
	s_andn2_b64 s[6:7], exec, s[20:21]
	v_addc_co_u32_e32 v139, vcc, -1, v169, vcc
	s_waitcnt vmcnt(0)
	ds_write_b128 v137, v[144:147]
	ds_write_b128 v142, v[148:151]
	global_load_dwordx4 v[144:147], v[138:139], off
	global_load_dwordx4 v[148:151], v[168:169], off
	s_waitcnt lgkmcnt(6)
	v_mfma_f32_32x32x16_bf16 v[238:253], v[178:181], v[186:189], 0
	ds_read_b128 v[178:181], v254 offset:64
	ds_read_b128 v[186:189], v211 offset:64
	s_waitcnt lgkmcnt(6)
	v_mfma_f32_32x32x16_bf16 v[238:253], v[182:185], v[190:193], v[238:253]
	ds_read_b128 v[182:185], v254 offset:96
	ds_read_b128 v[190:193], v211 offset:96
	s_waitcnt lgkmcnt(2)
	v_mfma_f32_32x32x16_bf16 v[238:253], v[178:181], v[186:189], v[238:253]
	ds_read_b128 v[178:181], v254 offset:128
	ds_read_b128 v[186:189], v211 offset:128
	s_waitcnt lgkmcnt(2)
	v_mfma_f32_32x32x16_bf16 v[238:253], v[182:185], v[190:193], v[238:253]
	ds_read_b128 v[182:185], v254 offset:160
	ds_read_b128 v[190:193], v211 offset:160
	v_mfma_f32_32x32x16_bf16 v[112:127], v[228:231], v[156:159], v[112:127]
	v_mfma_f32_32x32x16_bf16 v[96:111], v[228:231], v[132:135], v[96:111]
	ds_read_b128 v[228:231], v136 offset:9216
	s_nop 7
	v_mfma_f32_32x32x16_bf16 v[80:95], v[232:235], v[156:159], v[80:95]
	v_exp_f32_e32 v238, v238
	v_exp_f32_e32 v239, v239
	v_exp_f32_e32 v240, v240
	v_exp_f32_e32 v241, v241
	v_add_f32_e32 v174, v238, v239
	v_add_f32_e32 v175, v240, v241
	v_cvt_pk_bf16_f32 v194, v238, v239
	v_mfma_f32_32x32x16_bf16 v[64:79], v[232:235], v[132:135], v[64:79]
	ds_read_b128 v[232:235], v136 offset:13824
	v_cvt_pk_bf16_f32 v195, v240, v241
	v_exp_f32_e32 v242, v242
	v_exp_f32_e32 v243, v243
	v_exp_f32_e32 v244, v244
	v_exp_f32_e32 v245, v245
	v_add_f32_e32 v174, v174, v242
	v_add_f32_e32 v175, v175, v243
	s_waitcnt lgkmcnt(1)
	v_mfma_f32_32x32x16_bf16 v[32:47], v[228:231], v[156:159], v[32:47]
	v_add_f32_e32 v174, v174, v244
	v_add_f32_e32 v175, v175, v245
	v_cvt_pk_bf16_f32 v196, v242, v243
	v_cvt_pk_bf16_f32 v197, v244, v245
	v_exp_f32_e32 v246, v246
	v_exp_f32_e32 v247, v247
	v_exp_f32_e32 v248, v248
	v_mfma_f32_32x32x16_bf16 v[48:63], v[228:231], v[132:135], v[48:63]
	ds_read_b128 v[228:231], v136 offset:32
	v_exp_f32_e32 v249, v249
	v_add_f32_e32 v174, v174, v246
	v_add_f32_e32 v175, v175, v247
	v_add_f32_e32 v174, v174, v248
	v_add_f32_e32 v175, v175, v249
	v_cvt_pk_bf16_f32 v198, v246, v247
	v_cvt_pk_bf16_f32 v199, v248, v249
	s_waitcnt lgkmcnt(1)
	v_mfma_f32_32x32x16_bf16 v[16:31], v[232:235], v[156:159], v[16:31]
	v_exp_f32_e32 v250, v250
	v_exp_f32_e32 v251, v251
	v_exp_f32_e32 v252, v252
	v_exp_f32_e32 v253, v253
	v_add_f32_e32 v174, v174, v250
	v_add_f32_e32 v175, v175, v251
	v_mfma_f32_32x32x16_bf16 v[0:15], v[232:235], v[132:135], v[0:15]
	ds_read_b128 v[232:235], v136 offset:4640
	v_add_f32_e32 v174, v174, v252
	v_add_f32_e32 v175, v175, v253
	v_cvt_pk_bf16_f32 v200, v250, v251
	v_cvt_pk_bf16_f32 v201, v252, v253
	v_add_f32_e32 v174, v174, v175
	v_add_f32_e32 v165, v165, v174
	v_mfma_f32_32x32x16_bf16 v[238:253], v[178:181], v[186:189], 0
	ds_read_b128 v[178:181], v254 offset:192
	ds_read_b128 v[186:189], v211 offset:192
	v_mfma_f32_32x32x16_bf16 v[238:253], v[182:185], v[190:193], v[238:253]
	ds_read_b128 v[182:185], v254 offset:224
	ds_read_b128 v[190:193], v211 offset:224
	s_waitcnt lgkmcnt(2)
	v_mfma_f32_32x32x16_bf16 v[238:253], v[178:181], v[186:189], v[238:253]
	ds_read_b128 v[178:181], v254 offset:8704
	ds_read_b128 v[186:189], v211
	s_waitcnt lgkmcnt(2)
	v_mfma_f32_32x32x16_bf16 v[238:253], v[182:185], v[190:193], v[238:253]
	ds_read_b128 v[182:185], v254 offset:8736
	ds_read_b128 v[190:193], v211 offset:32
	v_mfma_f32_32x32x16_bf16 v[112:127], v[228:231], v[152:155], v[112:127]
	v_mfma_f32_32x32x16_bf16 v[96:111], v[228:231], v[128:131], v[96:111]
	ds_read_b128 v[228:231], v136 offset:9248
	s_nop 7
	v_mfma_f32_32x32x16_bf16 v[80:95], v[232:235], v[152:155], v[80:95]
	v_exp_f32_e32 v238, v238
	v_exp_f32_e32 v239, v239
	v_exp_f32_e32 v240, v240
	v_exp_f32_e32 v241, v241
	v_add_f32_e32 v174, v238, v239
	v_add_f32_e32 v175, v240, v241
	v_cvt_pk_bf16_f32 v202, v238, v239
	v_mfma_f32_32x32x16_bf16 v[64:79], v[232:235], v[128:131], v[64:79]
	ds_read_b128 v[232:235], v136 offset:13856
	v_cvt_pk_bf16_f32 v203, v240, v241
	v_exp_f32_e32 v242, v242
	v_exp_f32_e32 v243, v243
	v_exp_f32_e32 v244, v244
	v_exp_f32_e32 v245, v245
	v_add_f32_e32 v174, v174, v242
	v_add_f32_e32 v175, v175, v243
	s_waitcnt lgkmcnt(1)
	v_mfma_f32_32x32x16_bf16 v[32:47], v[228:231], v[152:155], v[32:47]
	v_add_f32_e32 v174, v174, v244
	v_add_f32_e32 v175, v175, v245
	v_cvt_pk_bf16_f32 v204, v242, v243
	v_cvt_pk_bf16_f32 v205, v244, v245
	v_exp_f32_e32 v246, v246
	v_exp_f32_e32 v247, v247
	v_exp_f32_e32 v248, v248
	v_mfma_f32_32x32x16_bf16 v[48:63], v[228:231], v[128:131], v[48:63]
	ds_read_b128 v[228:231], v217
	v_exp_f32_e32 v249, v249
	v_add_f32_e32 v174, v174, v246
	v_add_f32_e32 v175, v175, v247
	v_add_f32_e32 v174, v174, v248
	v_add_f32_e32 v175, v175, v249
	v_cvt_pk_bf16_f32 v206, v246, v247
	v_cvt_pk_bf16_f32 v207, v248, v249
	s_waitcnt lgkmcnt(1)
	v_mfma_f32_32x32x16_bf16 v[16:31], v[232:235], v[152:155], v[16:31]
	v_exp_f32_e32 v250, v250
	v_exp_f32_e32 v251, v251
	v_exp_f32_e32 v252, v252
	v_exp_f32_e32 v253, v253
	v_add_f32_e32 v174, v174, v250
	v_add_f32_e32 v175, v175, v251
	v_mfma_f32_32x32x16_bf16 v[0:15], v[232:235], v[128:131], v[0:15]
	ds_read_b128 v[232:235], v217 offset:4608
	v_add_f32_e32 v174, v174, v252
	v_add_f32_e32 v175, v175, v253
	v_cvt_pk_bf16_f32 v208, v250, v251
	v_cvt_pk_bf16_f32 v209, v252, v253
	v_add_f32_e32 v174, v174, v175
	v_add_f32_e32 v164, v164, v174
	s_waitcnt vmcnt(0)
	ds_write_b128 v218, v[144:147]
	ds_write_b128 v219, v[148:151]
	s_cmp_ge_u32 s34, s35
	s_cbranch_scc1 .Lattn_kskip_s
	v_lshl_add_u64 v[170:171], v[166:167], 0, s[22:23]
	v_add_co_u32_e32 v172, vcc, 0xc5c8000, v170
	s_nop 1
	v_addc_co_u32_e32 v173, vcc, 0, v171, vcc
	v_add_co_u32_e32 v170, vcc, 0xc5d8000, v170
	s_nop 1
	v_addc_co_u32_e32 v171, vcc, 0, v171, vcc
	global_load_dwordx4 v[144:147], v[172:173], off
	global_load_dwordx4 v[148:151], v[170:171], off
; #define LAS __attribute__((address_space(3)))
; #define SB0() __builtin_amdgcn_sched_barrier(0)
; template <bool SHIFT> DI void attn_unit(LAS unsigned char* lds, const bf16_t* Qb, const bf16_t* Kb, const bf16_t* Vt, bf16_t* concat,
;                   int b, int h, int qt, float shift2, float lam, int lam_init_bits, const float* subln_g) {
;     ...
;         const LAS unsigned char* vb = lds + V_OFF + vcur * V_BYTES + r * VP + hh * 16;
; #pragma unroll
;         for (int half = 0; half < 2; ++half) {
;             if (lag) PVH(Pc, vold);
;             QKEXP(Pc, half);
;             if (half == 0 && pf) { *(LAS u32x4*)(lds + V_OFF + vnx * V_BYTES + vrow0 * VP + vc * 16) = sg0; *(LAS u32x4*)(lds + V_OFF + vnx * V_BYTES + (vrow0 + 64) * VP + vc * 16) = sg1;
;                 if (kt + 2 < nkt) { sg0 = *(const u32x4*)(kg + (ko + 64 + krow0) * 1024 + kc * 8); sg1 = *(const u32x4*)(kg + (ko + 64 + krow0 + 32) * 1024 + kc * 8); } }
;             vold = vb + half * 64;
;             SB0();
;             if (!lag) PVH(Pc, vold);
;         }
;         __syncthreads();
;         vcur = vnx;
.Lattn_kskip_s:
	v_mfma_f32_32x32x16_bf16 v[238:253], v[178:181], v[186:189], 0
	ds_read_b128 v[178:181], v254 offset:8768
	ds_read_b128 v[186:189], v211 offset:64
	v_mfma_f32_32x32x16_bf16 v[238:253], v[182:185], v[190:193], v[238:253]
	ds_read_b128 v[182:185], v254 offset:8800
	ds_read_b128 v[190:193], v211 offset:96
	s_waitcnt lgkmcnt(2)
	v_mfma_f32_32x32x16_bf16 v[238:253], v[178:181], v[186:189], v[238:253]
	ds_read_b128 v[178:181], v254 offset:8832
	ds_read_b128 v[186:189], v211 offset:128
	s_waitcnt lgkmcnt(2)
	v_mfma_f32_32x32x16_bf16 v[238:253], v[182:185], v[190:193], v[238:253]
	ds_read_b128 v[182:185], v254 offset:8864
	ds_read_b128 v[190:193], v211 offset:160
	v_mfma_f32_32x32x16_bf16 v[112:127], v[228:231], v[194:197], v[112:127]
	v_mfma_f32_32x32x16_bf16 v[96:111], v[228:231], v[202:205], v[96:111]
	ds_read_b128 v[228:231], v217 offset:9216
	s_nop 7
	v_mfma_f32_32x32x16_bf16 v[80:95], v[232:235], v[194:197], v[80:95]
	v_exp_f32_e32 v238, v238
	v_exp_f32_e32 v239, v239
	v_exp_f32_e32 v240, v240
	v_exp_f32_e32 v241, v241
	v_add_f32_e32 v174, v238, v239
	v_add_f32_e32 v175, v240, v241
	v_cvt_pk_bf16_f32 v156, v238, v239
	v_mfma_f32_32x32x16_bf16 v[64:79], v[232:235], v[202:205], v[64:79]
	ds_read_b128 v[232:235], v217 offset:13824
	v_cvt_pk_bf16_f32 v157, v240, v241
	v_exp_f32_e32 v242, v242
	v_exp_f32_e32 v243, v243
	v_exp_f32_e32 v244, v244
	v_exp_f32_e32 v245, v245
	v_add_f32_e32 v174, v174, v242
	v_add_f32_e32 v175, v175, v243
	s_waitcnt lgkmcnt(1)
	v_mfma_f32_32x32x16_bf16 v[32:47], v[228:231], v[194:197], v[32:47]
	v_add_f32_e32 v174, v174, v244
	v_add_f32_e32 v175, v175, v245
	v_cvt_pk_bf16_f32 v158, v242, v243
	v_cvt_pk_bf16_f32 v159, v244, v245
	v_exp_f32_e32 v246, v246
	v_exp_f32_e32 v247, v247
	v_exp_f32_e32 v248, v248
	v_mfma_f32_32x32x16_bf16 v[48:63], v[228:231], v[202:205], v[48:63]
	ds_read_b128 v[228:231], v217 offset:32
	v_exp_f32_e32 v249, v249
	v_add_f32_e32 v174, v174, v246
	v_add_f32_e32 v175, v175, v247
	v_add_f32_e32 v174, v174, v248
	v_add_f32_e32 v175, v175, v249
	v_cvt_pk_bf16_f32 v152, v246, v247
	v_cvt_pk_bf16_f32 v153, v248, v249
	s_waitcnt lgkmcnt(1)
	v_mfma_f32_32x32x16_bf16 v[16:31], v[232:235], v[194:197], v[16:31]
	v_exp_f32_e32 v250, v250
	v_exp_f32_e32 v251, v251
	v_exp_f32_e32 v252, v252
	v_exp_f32_e32 v253, v253
	v_add_f32_e32 v174, v174, v250
	v_add_f32_e32 v175, v175, v251
	v_mfma_f32_32x32x16_bf16 v[0:15], v[232:235], v[202:205], v[0:15]
	ds_read_b128 v[232:235], v217 offset:4640
	v_add_f32_e32 v174, v174, v252
	v_add_f32_e32 v175, v175, v253
	v_cvt_pk_bf16_f32 v154, v250, v251
	v_cvt_pk_bf16_f32 v155, v252, v253
	v_add_f32_e32 v174, v174, v175
	v_add_f32_e32 v165, v165, v174
	v_mfma_f32_32x32x16_bf16 v[238:253], v[178:181], v[186:189], 0
	ds_read_b128 v[178:181], v254 offset:8896
	ds_read_b128 v[186:189], v211 offset:192
	v_mfma_f32_32x32x16_bf16 v[238:253], v[182:185], v[190:193], v[238:253]
	ds_read_b128 v[182:185], v254 offset:8928
	ds_read_b128 v[190:193], v211 offset:224
	s_waitcnt lgkmcnt(2)
	v_mfma_f32_32x32x16_bf16 v[238:253], v[178:181], v[186:189], v[238:253]
	s_waitcnt lgkmcnt(0)
	v_mfma_f32_32x32x16_bf16 v[238:253], v[182:185], v[190:193], v[238:253]
	v_mfma_f32_32x32x16_bf16 v[112:127], v[228:231], v[198:201], v[112:127]
	v_mfma_f32_32x32x16_bf16 v[96:111], v[228:231], v[206:209], v[96:111]
	ds_read_b128 v[228:231], v217 offset:9248
	s_nop 7
	v_mfma_f32_32x32x16_bf16 v[80:95], v[232:235], v[198:201], v[80:95]
	v_exp_f32_e32 v238, v238
	v_exp_f32_e32 v239, v239
	v_exp_f32_e32 v240, v240
	v_exp_f32_e32 v241, v241
	v_add_f32_e32 v174, v238, v239
	v_add_f32_e32 v175, v240, v241
	v_cvt_pk_bf16_f32 v132, v238, v239
	v_mfma_f32_32x32x16_bf16 v[64:79], v[232:235], v[206:209], v[64:79]
	ds_read_b128 v[232:235], v217 offset:13856
	v_cvt_pk_bf16_f32 v133, v240, v241
	v_exp_f32_e32 v242, v242
	v_exp_f32_e32 v243, v243
	v_exp_f32_e32 v244, v244
	v_exp_f32_e32 v245, v245
	v_add_f32_e32 v174, v174, v242
	v_add_f32_e32 v175, v175, v243
	s_waitcnt lgkmcnt(1)
	v_mfma_f32_32x32x16_bf16 v[32:47], v[228:231], v[198:201], v[32:47]
	v_add_f32_e32 v174, v174, v244
	v_add_f32_e32 v175, v175, v245
	v_cvt_pk_bf16_f32 v134, v242, v243
	v_cvt_pk_bf16_f32 v135, v244, v245
	v_exp_f32_e32 v246, v246
	v_exp_f32_e32 v247, v247
	v_exp_f32_e32 v248, v248
	v_mfma_f32_32x32x16_bf16 v[48:63], v[228:231], v[206:209], v[48:63]
	v_exp_f32_e32 v249, v249
	v_add_f32_e32 v174, v174, v246
	v_add_f32_e32 v175, v175, v247
	v_add_f32_e32 v174, v174, v248
	v_add_f32_e32 v175, v175, v249
	v_cvt_pk_bf16_f32 v128, v246, v247
	v_cvt_pk_bf16_f32 v129, v248, v249
	s_waitcnt lgkmcnt(0)
	v_mfma_f32_32x32x16_bf16 v[16:31], v[232:235], v[198:201], v[16:31]
	v_exp_f32_e32 v250, v250
	v_exp_f32_e32 v251, v251
	v_exp_f32_e32 v252, v252
	v_exp_f32_e32 v253, v253
	v_add_f32_e32 v174, v174, v250
	v_add_f32_e32 v175, v175, v251
	v_mfma_f32_32x32x16_bf16 v[0:15], v[232:235], v[206:209], v[0:15]
	v_add_f32_e32 v174, v174, v252
	v_add_f32_e32 v175, v175, v253
	v_cvt_pk_bf16_f32 v130, v250, v251
	v_cvt_pk_bf16_f32 v131, v252, v253
	v_add_f32_e32 v174, v174, v175
	v_add_f32_e32 v164, v164, v174
	s_waitcnt lgkmcnt(0)
	s_add_u32 s22, s22, 0x20000
	s_addc_u32 s23, s23, 0
	s_add_i32 s34, s34, 1
	v_add_u32_e32 v136, 64, v217
	s_cmp_eq_u32 s36, s22
	v_lshl_add_u64 v[168:169], v[168:169], 0, s[56:57]
	s_barrier
	s_cbranch_scc1 .LBB0_545
	s_mov_b32 s40, s65
	s_branch .LBB0_533
